# v68 + phase-0 weight-prep: hoisted descriptor scalar loads, 32 loads in flight per thread instead of 16 serialized round trips
# speedup vs baseline: 1.0179x; 1.0179x over previous
.LBB0_7:
	s_load_dword s2, s[0:1], 0x488
	v_mov_b32_e32 v13, v11
	s_waitcnt lgkmcnt(0)
	s_cmp_ge_i32 s82, s2
	s_cbranch_scc1 .LBB0_57
	v_and_b32_e32 v2, 63, v13
	v_ashrrev_i32_e32 v4, 6, v13
	s_movk_i32 s3, 0x104
	v_lshlrev_b32_e32 v6, 2, v2
	v_lshlrev_b32_e32 v1, 8, v2
	v_add_u32_e32 v8, 8, v4
	v_add_u32_e32 v10, 16, v4
	v_add_u32_e32 v12, 24, v4
	s_add_u32 s20, s0, 0x484
	v_mul_lo_u32 v16, v4, s3
	v_mov_b32_e32 v7, 0
	v_add3_u32 v20, 0, v6, v1
	v_mov_b32_e32 v1, v4
	v_mov_b32_e32 v3, v8
	v_mov_b32_e32 v5, v10
	v_mov_b32_e32 v9, v12
	v_ashrrev_i32_e32 v15, 31, v4
	v_mov_b32_e32 v14, v4
	s_addc_u32 s21, s1, 0
	v_add3_u32 v21, v16, v6, 0
	s_movk_i32 s3, 0x5ff
	s_movk_i32 s26, 0xe07
	s_movk_i32 s27, 0xe10
	s_movk_i32 s28, 0x4ff
	s_movk_i32 s29, 0x918
	s_movk_i32 s30, 0x7fff
	v_mov_b32_e32 v22, 1
	s_mov_b32 s31, s82
	s_load_dword s50, s[0:1], 0x184
	s_load_dword s51, s[0:1], 0x1b4
	s_load_dword s52, s[0:1], 0x1e4
	s_load_dword s53, s[0:1], 0x214
	s_load_dword s54, s[0:1], 0x244
	s_load_dword s55, s[0:1], 0x274
	s_load_dword s56, s[0:1], 0x2a4
	s_load_dword s57, s[0:1], 0x2d4
	s_load_dword s58, s[0:1], 0x304
	s_load_dword s59, s[0:1], 0x334
	s_load_dword s60, s[0:1], 0x364
	s_load_dword s61, s[0:1], 0x394
	s_load_dword s62, s[0:1], 0x3c4
	s_load_dword s63, s[0:1], 0x3f4
	s_load_dword s64, s[0:1], 0x424
	s_load_dword s65, s[0:1], 0x454
	s_load_dword s66, s[0:1], 0x484
	s_waitcnt lgkmcnt(0)
.LBB0_9:
	s_mov_b32 s6, 0
	s_cmp_lt_i32 s31, s50
	s_cselect_b32 s6, s6, 1
	s_cmp_lt_i32 s31, s51
	s_cselect_b32 s6, s6, 2
	s_cmp_lt_i32 s31, s52
	s_cselect_b32 s6, s6, 3
	s_cmp_lt_i32 s31, s53
	s_cselect_b32 s6, s6, 4
	s_cmp_lt_i32 s31, s54
	s_cselect_b32 s6, s6, 5
	s_cmp_lt_i32 s31, s55
	s_cselect_b32 s6, s6, 6
	s_cmp_lt_i32 s31, s56
	s_cselect_b32 s6, s6, 7
	s_cmp_lt_i32 s31, s57
	s_cselect_b32 s6, s6, 8
	s_cmp_lt_i32 s31, s58
	s_cselect_b32 s6, s6, 9
	s_cmp_lt_i32 s31, s59
	s_cselect_b32 s6, s6, 10
	s_cmp_lt_i32 s31, s60
	s_cselect_b32 s6, s6, 11
	s_cmp_lt_i32 s31, s61
	s_cselect_b32 s6, s6, 12
	s_cmp_lt_i32 s31, s62
	s_cselect_b32 s6, s6, 13
	s_cmp_lt_i32 s31, s63
	s_cselect_b32 s6, s6, 14
	s_cmp_lt_i32 s31, s64
	s_cselect_b32 s6, s6, 15
	s_cmp_lt_i32 s31, s65
	s_cselect_b32 s6, s6, 16
	s_cmp_lt_i32 s31, s66
	s_cselect_b32 s6, s6, 17
	s_mul_i32 s4, s6, 48
	s_mul_hi_u32 s5, s6, 48
	s_add_u32 s4, s0, s4
	s_addc_u32 s5, s1, s5
	s_load_dwordx4 s[8:11], s[4:5], 0x140
	s_load_dword s13, s[4:5], 0x154
	s_waitcnt lgkmcnt(0)
	s_ashr_i32 s33, s8, 31
	s_ashr_i32 s35, s10, 31
	s_lshr_b32 s6, s33, 26
	s_lshr_b32 s7, s35, 26
	s_add_i32 s6, s8, s6
	s_add_i32 s7, s10, s7
	s_ashr_i32 s6, s6, 6
	s_ashr_i32 s7, s7, 6
	s_mul_i32 s6, s7, s6
	s_abs_i32 s12, s6
	v_cvt_f32_u32_e32 v6, s12
	s_sub_i32 s22, s31, s13
	s_xor_b32 s14, s22, s6
	s_ashr_i32 s23, s14, 31
	v_rcp_iflag_f32_e32 v6, v6
	s_sub_i32 s14, 0, s12
	s_abs_i32 s13, s22
	v_mul_f32_e32 v6, 0x4f7ffffe, v6
	v_cvt_u32_f32_e32 v6, v6
	s_nop 0
	v_readfirstlane_b32 s15, v6
	s_mul_i32 s14, s14, s15
	s_mul_hi_u32 s14, s15, s14
	s_add_i32 s15, s15, s14
	s_mul_hi_u32 s14, s13, s15
	s_mul_i32 s15, s14, s12
	s_sub_i32 s13, s13, s15
	s_add_i32 s24, s14, 1
	s_sub_i32 s15, s13, s12
	s_cmp_ge_u32 s13, s12
	s_cselect_b32 s14, s24, s14
	s_cselect_b32 s13, s15, s13
	s_add_i32 s15, s14, 1
	s_cmp_ge_u32 s13, s12
	s_cselect_b32 s24, s15, s14
	s_abs_i32 s25, s7
	v_cvt_f32_u32_e32 v6, s25
	s_xor_b32 s24, s24, s23
	s_sub_i32 s24, s24, s23
	s_mul_i32 s6, s6, s24
	v_rcp_iflag_f32_e32 v6, v6
	s_sub_i32 s23, 0, s25
	s_sub_i32 s6, s22, s6
	s_xor_b32 s22, s6, s7
	v_mul_f32_e32 v6, 0x4f7ffffe, v6
	v_cvt_u32_f32_e32 v6, v6
	s_ashr_i32 s36, s22, 31
	s_abs_i32 s22, s6
	s_load_dwordx4 s[12:15], s[4:5], 0x128
	v_readfirstlane_b32 s34, v6
	s_mul_i32 s23, s23, s34
	s_mul_hi_u32 s23, s34, s23
	s_add_i32 s34, s34, s23
	s_mul_hi_u32 s23, s22, s34
	s_mul_i32 s34, s23, s25
	s_sub_i32 s22, s22, s34
	s_add_i32 s34, s23, 1
	s_sub_i32 s37, s22, s25
	s_cmp_ge_u32 s22, s25
	s_cselect_b32 s23, s34, s23
	s_cselect_b32 s22, s37, s22
	s_add_i32 s34, s23, 1
	s_cmp_ge_u32 s22, s25
	s_cselect_b32 s22, s34, s23
	s_xor_b32 s37, s22, s36
	s_sub_i32 s25, s37, s36
	s_mul_i32 s7, s25, s7
	s_sub_i32 s6, s6, s7
	s_lshl_b32 s34, s6, 6
	s_cmp_lt_i32 s11, 1
	v_or_b32_e32 v6, s34, v2
	s_cbranch_scc1 .LBB0_26
	s_cmp_eq_u32 s11, 1
	s_mov_b64 s[6:7], -1
	s_cbranch_scc0 .LBB0_25
	v_cmp_lt_i32_e32 vcc, s3, v6
	v_mov_b32_e32 v16, v6
	s_and_saveexec_b64 s[6:7], vcc
	s_cbranch_execz .LBB0_24
	s_cmpk_gt_u32 s34, 0xdff
	s_mov_b64 s[22:23], -1
	s_cbranch_scc0 .LBB0_22
	v_cmp_lt_u32_e32 vcc, s26, v6
	s_and_saveexec_b64 s[22:23], vcc
	s_xor_b64 s[22:23], exec, s[22:23]
	v_cmp_gt_u32_e32 vcc, s27, v6
	s_nop 1
	v_cndmask_b32_e32 v16, -1, v6, vcc
	s_andn2_saveexec_b64 s[22:23], s[22:23]
	v_add_u32_e32 v16, 0xfffff800, v6
	s_or_b64 exec, exec, s[22:23]
	s_mov_b64 s[22:23], 0

.LBB0_36:
	s_mul_i32 s23, s24, s8
	s_ashr_i32 s6, s9, 31
	s_mul_hi_i32 s41, s24, s8
	s_mul_i32 s6, s23, s6
	s_mul_hi_u32 s7, s23, s9
	s_lshl_b32 s22, s25, 6
	s_add_i32 s6, s7, s6
	s_mul_i32 s7, s41, s9
	s_load_dwordx2 s[24:25], s[4:5], 0x138
	s_add_i32 s7, s6, s7
	s_mul_i32 s6, s23, s9
	s_lshl_b64 s[6:7], s[6:7], 2
	s_waitcnt lgkmcnt(0)
	s_add_u32 s6, s12, s6
	s_addc_u32 s7, s13, s7
	v_cmp_gt_i32_e32 vcc, s9, v16
	s_cmp_lg_u64 s[24:25], 0
	s_mov_b32 s11, s8
	s_mov_b32 s42, s9
	v_cndmask_b32_e32 v6, -1, v16, vcc
	s_cselect_b64 s[8:9], -1, 0
	s_add_i32 s12, s22, s23
	v_lshl_add_u64 v[16:17], v[6:7], 2, s[6:7]
	s_ashr_i32 s13, s12, 31
	s_lshl_b32 s6, s37, 6
	v_lshl_add_u64 v[18:19], v[14:15], 0, s[12:13]
	s_add_i32 s6, s6, s23
	v_lshl_add_u64 v[18:19], v[18:19], 2, s[24:25]
	v_add_u32_e32 v23, s6, v14
	s_lshl_b32 s6, s36, 6
	v_cmp_lt_i32_e64 s[4:5], -1, v6
	v_add_u32_e32 v6, s22, v14
	v_lshl_add_u64 v[18:19], v[18:19], 0, 32
	v_subrev_u32_e32 v23, s6, v23
	s_mov_b32 s36, 0
	v_cndmask_b32_e64 v24, 0, 1, s[8:9]
	v_mov_b32_e32 v25, v21
	v_mov_b32_e32 v64, 1.0
	v_mov_b32_e32 v65, 1.0
	v_mov_b32_e32 v66, 1.0
	v_mov_b32_e32 v67, 1.0
	v_mov_b32_e32 v68, 1.0
	v_mov_b32_e32 v69, 1.0
	v_mov_b32_e32 v70, 1.0
	v_mov_b32_e32 v71, 1.0
	v_mov_b32_e32 v72, 1.0
	v_mov_b32_e32 v73, 1.0
	v_mov_b32_e32 v74, 1.0
	v_mov_b32_e32 v75, 1.0
	v_mov_b32_e32 v76, 1.0
	v_mov_b32_e32 v77, 1.0
	v_mov_b32_e32 v78, 1.0
	v_mov_b32_e32 v79, 1.0
	s_andn2_b64 vcc, exec, s[8:9]
	s_cbranch_vccnz .Lprep_nosc
	global_load_dword v64, v[18:19], off offset:-32
	global_load_dword v65, v[18:19], off offset:-16
	global_load_dword v66, v[18:19], off
	global_load_dword v67, v[18:19], off offset:16
	global_load_dword v68, v[18:19], off offset:32
	global_load_dword v69, v[18:19], off offset:48
	global_load_dword v70, v[18:19], off offset:64
	global_load_dword v71, v[18:19], off offset:80
	global_load_dword v72, v[18:19], off offset:96
	global_load_dword v73, v[18:19], off offset:112
	global_load_dword v74, v[18:19], off offset:128
	global_load_dword v75, v[18:19], off offset:144
	global_load_dword v76, v[18:19], off offset:160
	global_load_dword v77, v[18:19], off offset:176
	global_load_dword v78, v[18:19], off offset:192
	global_load_dword v79, v[18:19], off offset:208
.Lprep_nosc:
	v_mov_b32_e32 v80, 0
	v_mov_b32_e32 v81, 0
	v_mov_b32_e32 v82, 0
	v_mov_b32_e32 v83, 0
	v_mov_b32_e32 v84, 0
	v_mov_b32_e32 v85, 0
	v_mov_b32_e32 v86, 0
	v_mov_b32_e32 v87, 0
	v_mov_b32_e32 v88, 0
	v_mov_b32_e32 v89, 0
	v_mov_b32_e32 v90, 0
	v_mov_b32_e32 v91, 0
	v_mov_b32_e32 v92, 0
	v_mov_b32_e32 v93, 0
	v_mov_b32_e32 v94, 0
	v_mov_b32_e32 v95, 0
	s_and_saveexec_b64 s[12:13], s[4:5]
	v_mad_i64_i32 v[98:99], s[44:45], v6, s42, 0
	v_lshl_add_u64 v[98:99], v[98:99], 2, v[16:17]
	global_load_dword v80, v[98:99], off
	v_add_u32_e32 v96, 4, v6
	v_mad_i64_i32 v[98:99], s[44:45], v96, s42, 0
	v_lshl_add_u64 v[98:99], v[98:99], 2, v[16:17]
	global_load_dword v81, v[98:99], off
	v_add_u32_e32 v96, 8, v6
	v_mad_i64_i32 v[98:99], s[44:45], v96, s42, 0
	v_lshl_add_u64 v[98:99], v[98:99], 2, v[16:17]
	global_load_dword v82, v[98:99], off
	v_add_u32_e32 v96, 12, v6
	v_mad_i64_i32 v[98:99], s[44:45], v96, s42, 0
	v_lshl_add_u64 v[98:99], v[98:99], 2, v[16:17]
	global_load_dword v83, v[98:99], off
	v_add_u32_e32 v96, 16, v6
	v_mad_i64_i32 v[98:99], s[44:45], v96, s42, 0
	v_lshl_add_u64 v[98:99], v[98:99], 2, v[16:17]
	global_load_dword v84, v[98:99], off
	v_add_u32_e32 v96, 20, v6
	v_mad_i64_i32 v[98:99], s[44:45], v96, s42, 0
	v_lshl_add_u64 v[98:99], v[98:99], 2, v[16:17]
	global_load_dword v85, v[98:99], off
	v_add_u32_e32 v96, 24, v6
	v_mad_i64_i32 v[98:99], s[44:45], v96, s42, 0
	v_lshl_add_u64 v[98:99], v[98:99], 2, v[16:17]
	global_load_dword v86, v[98:99], off
	v_add_u32_e32 v96, 28, v6
	v_mad_i64_i32 v[98:99], s[44:45], v96, s42, 0
	v_lshl_add_u64 v[98:99], v[98:99], 2, v[16:17]
	global_load_dword v87, v[98:99], off
	v_add_u32_e32 v96, 32, v6
	v_mad_i64_i32 v[98:99], s[44:45], v96, s42, 0
	v_lshl_add_u64 v[98:99], v[98:99], 2, v[16:17]
	global_load_dword v88, v[98:99], off
	v_add_u32_e32 v96, 36, v6
	v_mad_i64_i32 v[98:99], s[44:45], v96, s42, 0
	v_lshl_add_u64 v[98:99], v[98:99], 2, v[16:17]
	global_load_dword v89, v[98:99], off
	v_add_u32_e32 v96, 40, v6
	v_mad_i64_i32 v[98:99], s[44:45], v96, s42, 0
	v_lshl_add_u64 v[98:99], v[98:99], 2, v[16:17]
	global_load_dword v90, v[98:99], off
	v_add_u32_e32 v96, 44, v6
	v_mad_i64_i32 v[98:99], s[44:45], v96, s42, 0
	v_lshl_add_u64 v[98:99], v[98:99], 2, v[16:17]
	global_load_dword v91, v[98:99], off
	v_add_u32_e32 v96, 48, v6
	v_mad_i64_i32 v[98:99], s[44:45], v96, s42, 0
	v_lshl_add_u64 v[98:99], v[98:99], 2, v[16:17]
	global_load_dword v92, v[98:99], off
	v_add_u32_e32 v96, 52, v6
	v_mad_i64_i32 v[98:99], s[44:45], v96, s42, 0
	v_lshl_add_u64 v[98:99], v[98:99], 2, v[16:17]
	global_load_dword v93, v[98:99], off
	v_add_u32_e32 v96, 56, v6
	v_mad_i64_i32 v[98:99], s[44:45], v96, s42, 0
	v_lshl_add_u64 v[98:99], v[98:99], 2, v[16:17]
	global_load_dword v94, v[98:99], off
	v_add_u32_e32 v96, 60, v6
	v_mad_i64_i32 v[98:99], s[44:45], v96, s42, 0
	v_lshl_add_u64 v[98:99], v[98:99], 2, v[16:17]
	global_load_dword v95, v[98:99], off
	s_waitcnt vmcnt(0)
	v_mul_f32_e32 v80, v64, v80
	v_mul_f32_e32 v81, v65, v81
	v_mul_f32_e32 v82, v66, v82
	v_mul_f32_e32 v83, v67, v83
	v_mul_f32_e32 v84, v68, v84
	v_mul_f32_e32 v85, v69, v85
	v_mul_f32_e32 v86, v70, v86
	v_mul_f32_e32 v87, v71, v87
	v_mul_f32_e32 v88, v72, v88
	v_mul_f32_e32 v89, v73, v89
	v_mul_f32_e32 v90, v74, v90
	v_mul_f32_e32 v91, v75, v91
	v_mul_f32_e32 v92, v76, v92
	v_mul_f32_e32 v93, v77, v93
	v_mul_f32_e32 v94, v78, v94
	v_mul_f32_e32 v95, v79, v95
	s_or_b64 exec, exec, s[12:13]
	ds_write_b32 v21, v80
	ds_write_b32 v21, v81 offset:1040
	ds_write_b32 v21, v82 offset:2080
	ds_write_b32 v21, v83 offset:3120
	ds_write_b32 v21, v84 offset:4160
	ds_write_b32 v21, v85 offset:5200
	ds_write_b32 v21, v86 offset:6240
	ds_write_b32 v21, v87 offset:7280
	ds_write_b32 v21, v88 offset:8320
	ds_write_b32 v21, v89 offset:9360
	ds_write_b32 v21, v90 offset:10400
	ds_write_b32 v21, v91 offset:11440
	ds_write_b32 v21, v92 offset:12480
	ds_write_b32 v21, v93 offset:13520
	ds_write_b32 v21, v94 offset:14560
	ds_write_b32 v21, v95 offset:15600
